# strategy 7.12: __all(en) ballot trimmed to one s_cmp_eq_u64 vcc, exec in the NSA stream steps
# speedup vs baseline: 1.0056x; 1.0056x over previous
; #define LAS __attribute__((address_space(3)))
; __device__ __forceinline__ void qk_tile(f32x16& p0, f32x16& p1, const ldsp Kt, const bf16x8 (&qr)[4], const f32x16& cin, int r32, int hi) {
;     const ldsp kb = Kt + hi * 1024; const int ks = (r32 ^ (2 * hi)) << 4;
; #pragma unroll
;     for (int d0 = 0; d0 < 4; ++d0) {
;         const ldsp kp = kb + d0 * 2048 + (ks ^ (64 * d0));
;         const bf16x8 b0 = *(const LAS bf16x8*)(kp), b1 = *(const LAS bf16x8*)(kp + 512);
;         if (d0 == 0) { p0 = __builtin_amdgcn_mfma_f32_32x32x16_bf16(b0, qr[0], cin, 0, 0, 0); p1 = __builtin_amdgcn_mfma_f32_32x32x16_bf16(b1, qr[0], cin, 0, 0, 0); }
;         else { p0 = __builtin_amdgcn_mfma_f32_32x32x16_bf16(b0, qr[d0], p0, 0, 0, 0); p1 = __builtin_amdgcn_mfma_f32_32x32x16_bf16(b1, qr[d0], p1, 0, 0, 0); }
;     }
;     asm volatile("s_nop 15\n\ts_nop 7" : "+v"(p0), "+v"(p1));
.LBB0_720:
	s_add_i32 s71, s81, -4
	s_cmp_gt_u32 s71, s93
	s_cselect_b64 s[6:7], -1, 0
	s_and_b64 s[10:11], s[6:7], exec
	s_cselect_b32 s9, s79, 0
	s_add_i32 s10, s71, s9
	s_lshl_b64 s[12:13], 1, s10
	v_and_b32_e32 v65, s13, v165
	v_and_b32_e32 v64, s12, v164
	v_cmp_ne_u64_e32 vcc, 0, v[64:65]
	s_or_b64 vcc, s[6:7], vcc
	s_cbranch_vccz .LBB0_746
	s_add_i32 s72, s8, 0
	s_add_i32 s72, s72, 0x10000
	v_add_u32_e32 v72, s72, v185
	v_add_u32_e32 v68, v72, v186
	ds_read_b128 v[64:67], v68
	ds_read_b128 v[68:71], v68 offset:512
	s_waitcnt lgkmcnt(0)
	v_mfma_f32_32x32x16_bf16 v[112:127], v[64:67], v[136:139], v[48:63]
	v_mfma_f32_32x32x16_bf16 v[96:111], v[68:71], v[136:139], v[48:63]
	v_add_u32_e32 v68, v72, v187
	ds_read_b128 v[64:67], v68 offset:2048
	ds_read_b128 v[68:71], v68 offset:2560
	s_waitcnt lgkmcnt(1)
	v_mfma_f32_32x32x16_bf16 v[112:127], v[64:67], v[128:131], v[112:127]
	s_waitcnt lgkmcnt(0)
	v_mfma_f32_32x32x16_bf16 v[96:111], v[68:71], v[128:131], v[96:111]
	v_add_u32_e32 v68, v72, v188
	ds_read_b128 v[64:67], v68 offset:4096
	ds_read_b128 v[68:71], v68 offset:4608
	s_waitcnt lgkmcnt(1)
	v_mfma_f32_32x32x16_bf16 v[112:127], v[64:67], v[132:135], v[112:127]
	s_waitcnt lgkmcnt(0)
	v_mfma_f32_32x32x16_bf16 v[96:111], v[68:71], v[132:135], v[96:111]
	v_add_u32_e32 v68, v72, v189
	ds_read_b128 v[64:67], v68 offset:6144
	ds_read_b128 v[68:71], v68 offset:6656
	s_waitcnt lgkmcnt(1)
	v_mfma_f32_32x32x16_bf16 v[112:127], v[64:67], v[140:143], v[112:127]
	s_cmp_eq_u64 vcc, exec
	s_waitcnt lgkmcnt(0)
	v_mfma_f32_32x32x16_bf16 v[96:111], v[68:71], v[140:143], v[96:111]
	s_nop 15
	s_nop 7
	s_cbranch_scc1 .LBB0_723
	v_cndmask_b32_e64 v64, v168, 0, vcc
	s_nop 4
	v_pk_add_f32 v[126:127], v[64:65], v[126:127] op_sel_hi:[0,1]
	v_pk_add_f32 v[124:125], v[64:65], v[124:125] op_sel_hi:[0,1]
	v_pk_add_f32 v[122:123], v[64:65], v[122:123] op_sel_hi:[0,1]
	v_pk_add_f32 v[120:121], v[64:65], v[120:121] op_sel_hi:[0,1]
	v_pk_add_f32 v[118:119], v[64:65], v[118:119] op_sel_hi:[0,1]
	v_pk_add_f32 v[116:117], v[64:65], v[116:117] op_sel_hi:[0,1]
	v_pk_add_f32 v[114:115], v[64:65], v[114:115] op_sel_hi:[0,1]
	v_pk_add_f32 v[112:113], v[64:65], v[112:113] op_sel_hi:[0,1]
	v_pk_add_f32 v[110:111], v[64:65], v[110:111] op_sel_hi:[0,1]
	v_pk_add_f32 v[108:109], v[64:65], v[108:109] op_sel_hi:[0,1]
	v_pk_add_f32 v[106:107], v[64:65], v[106:107] op_sel_hi:[0,1]
	v_pk_add_f32 v[104:105], v[64:65], v[104:105] op_sel_hi:[0,1]
	v_pk_add_f32 v[102:103], v[64:65], v[102:103] op_sel_hi:[0,1]
	v_pk_add_f32 v[100:101], v[64:65], v[100:101] op_sel_hi:[0,1]
	v_pk_add_f32 v[98:99], v[64:65], v[98:99] op_sel_hi:[0,1]
	v_pk_add_f32 v[96:97], v[64:65], v[96:97] op_sel_hi:[0,1]

; #define LAS __attribute__((address_space(3)))
; __device__ __forceinline__ void qk_tile(f32x16& p0, f32x16& p1, const ldsp Kt, const bf16x8 (&qr)[4], const f32x16& cin, int r32, int hi) {
;     const ldsp kb = Kt + hi * 1024; const int ks = (r32 ^ (2 * hi)) << 4;
; #pragma unroll
;     for (int d0 = 0; d0 < 4; ++d0) {
;         const ldsp kp = kb + d0 * 2048 + (ks ^ (64 * d0));
;         const bf16x8 b0 = *(const LAS bf16x8*)(kp), b1 = *(const LAS bf16x8*)(kp + 512);
;         if (d0 == 0) { p0 = __builtin_amdgcn_mfma_f32_32x32x16_bf16(b0, qr[0], cin, 0, 0, 0); p1 = __builtin_amdgcn_mfma_f32_32x32x16_bf16(b1, qr[0], cin, 0, 0, 0); }
;         else { p0 = __builtin_amdgcn_mfma_f32_32x32x16_bf16(b0, qr[d0], p0, 0, 0, 0); p1 = __builtin_amdgcn_mfma_f32_32x32x16_bf16(b1, qr[d0], p1, 0, 0, 0); }
;     }
;     asm volatile("s_nop 15\n\ts_nop 7" : "+v"(p0), "+v"(p1));
.LBB0_756:
	s_cmp_ge_u32 s71, s93
	s_cselect_b64 s[6:7], -1, 0
	s_and_b64 s[10:11], s[6:7], exec
	s_cselect_b32 s9, s79, 0
	s_add_i32 s10, s9, s81
	s_add_i32 s10, s10, -3
	s_lshl_b64 s[12:13], 1, s10
	v_and_b32_e32 v65, s13, v165
	v_and_b32_e32 v64, s12, v164
	v_cmp_ne_u64_e32 vcc, 0, v[64:65]
	s_or_b64 vcc, s[6:7], vcc
	s_cbranch_vccz .LBB0_783
	s_add_i32 s70, s8, 0
	s_add_i32 s70, s70, 0x10000
	v_add_u32_e32 v72, s70, v185
	v_add_u32_e32 v68, v72, v186
	ds_read_b128 v[64:67], v68
	ds_read_b128 v[68:71], v68 offset:512
	s_waitcnt lgkmcnt(1)
	v_mfma_f32_32x32x16_bf16 v[112:127], v[64:67], v[136:139], v[48:63]
	s_waitcnt lgkmcnt(0)
	v_mfma_f32_32x32x16_bf16 v[96:111], v[68:71], v[136:139], v[48:63]
	v_add_u32_e32 v68, v72, v187
	ds_read_b128 v[64:67], v68 offset:2048
	ds_read_b128 v[68:71], v68 offset:2560
	s_waitcnt lgkmcnt(1)
	v_mfma_f32_32x32x16_bf16 v[112:127], v[64:67], v[128:131], v[112:127]
	s_waitcnt lgkmcnt(0)
	v_mfma_f32_32x32x16_bf16 v[96:111], v[68:71], v[128:131], v[96:111]
	v_add_u32_e32 v68, v72, v188
	ds_read_b128 v[64:67], v68 offset:4096
	ds_read_b128 v[68:71], v68 offset:4608
	s_waitcnt lgkmcnt(1)
	v_mfma_f32_32x32x16_bf16 v[112:127], v[64:67], v[132:135], v[112:127]
	s_waitcnt lgkmcnt(0)
	v_mfma_f32_32x32x16_bf16 v[96:111], v[68:71], v[132:135], v[96:111]
	v_add_u32_e32 v68, v72, v189
	ds_read_b128 v[64:67], v68 offset:6144
	ds_read_b128 v[68:71], v68 offset:6656
	s_waitcnt lgkmcnt(1)
	v_mfma_f32_32x32x16_bf16 v[112:127], v[64:67], v[140:143], v[112:127]
	s_cmp_eq_u64 vcc, exec
	s_waitcnt lgkmcnt(0)
	v_mfma_f32_32x32x16_bf16 v[96:111], v[68:71], v[140:143], v[96:111]
	s_nop 15
	s_nop 7
	s_cbranch_scc1 .LBB0_759
	v_cndmask_b32_e64 v64, v168, 0, vcc
	s_nop 4
	v_pk_add_f32 v[126:127], v[64:65], v[126:127] op_sel_hi:[0,1]
	v_pk_add_f32 v[124:125], v[64:65], v[124:125] op_sel_hi:[0,1]
	v_pk_add_f32 v[122:123], v[64:65], v[122:123] op_sel_hi:[0,1]
	v_pk_add_f32 v[120:121], v[64:65], v[120:121] op_sel_hi:[0,1]
	v_pk_add_f32 v[118:119], v[64:65], v[118:119] op_sel_hi:[0,1]
	v_pk_add_f32 v[116:117], v[64:65], v[116:117] op_sel_hi:[0,1]
	v_pk_add_f32 v[114:115], v[64:65], v[114:115] op_sel_hi:[0,1]
	v_pk_add_f32 v[112:113], v[64:65], v[112:113] op_sel_hi:[0,1]
	v_pk_add_f32 v[110:111], v[64:65], v[110:111] op_sel_hi:[0,1]
	v_pk_add_f32 v[108:109], v[64:65], v[108:109] op_sel_hi:[0,1]
	v_pk_add_f32 v[106:107], v[64:65], v[106:107] op_sel_hi:[0,1]
	v_pk_add_f32 v[104:105], v[64:65], v[104:105] op_sel_hi:[0,1]
	v_pk_add_f32 v[102:103], v[64:65], v[102:103] op_sel_hi:[0,1]
	v_pk_add_f32 v[100:101], v[64:65], v[100:101] op_sel_hi:[0,1]
	v_pk_add_f32 v[98:99], v[64:65], v[98:99] op_sel_hi:[0,1]
	v_pk_add_f32 v[96:97], v[64:65], v[96:97] op_sel_hi:[0,1]
